# stack: first K/V tile loads issued before Q staging, softmax alpha-skip and shorter row-sum tail, scan helper DPP reductions folded into v_add_f32_dpp; on top of static-priority version
# baseline (speedup 1.0000x reference)
; __device__ __forceinline__ unsigned pk_bf16(float lo, float hi) { const f32x2 v = {lo, hi}; return __builtin_bit_cast(unsigned, __builtin_convertvector(v, nbf16x2)); }
; #define UNPK(w) ((f32x4){bflo((w).x), bfhi((w).x), bflo((w).y), bfhi((w).y)})
; #define ROWSUM16(v) { v += dpp_f(v, 0); v += dpp_f(v, 1); v += dpp_f(v, 2); v += dpp_f(v, 3); }
; __device__ __forceinline__ void phase_scan(const Args& a, unsigned char* lds) {
;     ...
;                 if (it >= 2) {
;                     const int c = it - 2, buf = c & 1;
; #pragma unroll
;                     for (int pp = 0; pp < 2; ++pp) { const int s = (2 * hw + pp) * 4 + hss;
;                         const int row = row0 + c * 16 + s;
;                         const f32x4 y = *(const f32x4*)(ybuf + ((buf * 2 + hd) * 16 + s) * 64 + hc4);
;                         float sm = (y[0] + y[1]) + (y[2] + y[3]); ROWSUM16(sm)
;                         const float mean = sm * (1.f / 64.f);
;                         const f32x4 d = y - mean;
;                         float sq = (d[0] * d[0] + d[1] * d[1]) + (d[2] * d[2] + d[3] * d[3]); ROWSUM16(sq)
;                         const float rs = rsqrtf(sq * (1.f / 64.f) + 64e-5f);
;                         const f32x4 vv = *(const f32x4*)(vec + (size_t)((buf * 2 + hd) * 16 + s) * 384 + 128 + hc4);
;                         const float bo = bon[(buf * 2 + hd) * 16 + s];
;                         const f32x4 g = UNPK(__builtin_bit_cast(u32x2, PFU(pp, 8)));
;                         const f32x4 o = (d * rs * lnw + lnb + bo * vv) * g;
;                         *(u32x2*)(BRc + (size_t)row * BR + hcol4) = (u32x2){pk_bf16(o[0], o[1]), pk_bf16(o[2], o[3])};
;                     }
.LBB0_641:
	s_lshl_b32 s56, s71, 1
	s_and_b32 s56, s56, 2
	v_add_lshl_u32 v137, s56, v75, 4
	v_or_b32_e32 v151, v137, v126
	v_lshl_add_u32 v138, v151, 8, v128
	ds_read_b128 v[138:141], v138
	v_mad_u64_u32 v[142:143], s[56:57], v151, s63, v[66:67]
	ds_read_b128 v[142:145], v142 offset:512
	v_or_b32_e32 v157, v137, v129
	s_waitcnt lgkmcnt(0)
	v_mov_b32_e32 v146, v139
	v_mov_b32_e32 v147, v140
	v_mov_b32_e32 v148, v138
	v_mov_b32_e32 v149, v141
	v_pk_add_f32 v[146:147], v[146:147], v[148:149]
	v_lshl_add_u32 v137, v157, 8, v128
	v_add_f32_e32 v146, v146, v147
	v_lshlrev_b32_e32 v158, 16, v136
	v_and_b32_e32 v159, 0xffff0000, v136
	v_add_f32_dpp v146, v146, v146 quad_perm:[1,0,3,2] row_mask:0xf bank_mask:0xf
	v_lshlrev_b32_e32 v154, 16, v135
	v_and_b32_e32 v155, 0xffff0000, v135
	v_add_f32_dpp v146, v146, v146 quad_perm:[2,3,0,1] row_mask:0xf bank_mask:0xf
	v_add_u32_e32 v65, s72, v77
	v_or_b32_e32 v150, v65, v126
	v_add_f32_dpp v146, v146, v146 row_ror:4 row_mask:0xf bank_mask:0xf
	s_nop 1
	v_add_f32_dpp v146, v146, v146 row_ror:8 row_mask:0xf bank_mask:0xf
	v_fmamk_f32 v139, v146, 0xbc800000, v139
	v_fmamk_f32 v138, v146, 0xbc800000, v138
	v_fmamk_f32 v141, v146, 0xbc800000, v141
	v_fmac_f32_e32 v140, 0xbc800000, v146
	v_pk_mul_f32 v[146:147], v[140:141], v[140:141]
	v_pk_mul_f32 v[148:149], v[138:139], v[138:139]
	s_nop 0
	v_pk_mov_b32 v[152:153], v[148:149], v[146:147] op_sel:[1,0]
	v_mov_b32_e32 v149, v147
	v_lshl_add_u32 v146, v151, 2, s64
	v_pk_add_f32 v[152:153], v[152:153], v[148:149]
	ds_read_b32 v156, v146
	ds_read_b128 v[146:149], v137
	v_ashrrev_i32_e32 v151, 31, v150
	v_lshlrev_b64 v[150:151], 12, v[150:151]
	v_lshl_add_u64 v[150:151], v[86:87], 0, v[150:151]
	s_waitcnt lgkmcnt(0)
	v_mov_b32_e32 v136, v147
	v_mov_b32_e32 v137, v148
	v_mov_b32_e32 v160, v146
	v_mov_b32_e32 v161, v149
	v_pk_add_f32 v[136:137], v[136:137], v[160:161]
	s_nop 0
	v_add_f32_e32 v135, v136, v137
	s_nop 1
	v_add_f32_dpp v135, v135, v135 quad_perm:[1,0,3,2] row_mask:0xf bank_mask:0xf
	s_nop 1
	v_add_f32_dpp v135, v135, v135 quad_perm:[2,3,0,1] row_mask:0xf bank_mask:0xf
	s_nop 1
	v_add_f32_dpp v135, v135, v135 row_ror:4 row_mask:0xf bank_mask:0xf
	s_nop 1
	v_add_f32_dpp v135, v135, v135 row_ror:8 row_mask:0xf bank_mask:0xf
	v_fmamk_f32 v147, v135, 0xbc800000, v147
	v_fmamk_f32 v146, v135, 0xbc800000, v146
	v_fmamk_f32 v149, v135, 0xbc800000, v149
	v_fmac_f32_e32 v148, 0xbc800000, v135
	v_pk_mul_f32 v[136:137], v[148:149], v[148:149]
	v_pk_mul_f32 v[160:161], v[146:147], v[146:147]
	s_nop 0
	v_pk_mov_b32 v[162:163], v[160:161], v[136:137] op_sel:[1,0]
	v_mov_b32_e32 v161, v137
	v_pk_add_f32 v[136:137], v[162:163], v[160:161]
	v_mov_b32_e32 v161, v152
	v_mov_b32_e32 v160, v136
	v_mov_b32_e32 v152, v137
	v_pk_add_f32 v[136:137], v[160:161], v[152:153]
	s_nop 0
	v_mov_b32_e32 v153, v137
	v_mov_b32_e32 v152, v136
	s_nop 0
	v_mov_b32_dpp v153, v153 quad_perm:[1,0,3,2] row_mask:0xf bank_mask:0xf
	v_mov_b32_dpp v152, v152 quad_perm:[1,0,3,2] row_mask:0xf bank_mask:0xf
	v_pk_add_f32 v[136:137], v[136:137], v[152:153]
	s_nop 0
	v_mov_b32_e32 v153, v137
	v_mov_b32_e32 v152, v136
	s_nop 0
	v_mov_b32_dpp v153, v153 quad_perm:[2,3,0,1] row_mask:0xf bank_mask:0xf
	v_mov_b32_dpp v152, v152 quad_perm:[2,3,0,1] row_mask:0xf bank_mask:0xf
	v_pk_add_f32 v[136:137], v[136:137], v[152:153]
	s_nop 0
	v_mov_b32_e32 v153, v137
	v_mov_b32_e32 v152, v136
	s_nop 0
	v_mov_b32_dpp v153, v153 row_ror:4 row_mask:0xf bank_mask:0xf
	v_mov_b32_dpp v152, v152 row_ror:4 row_mask:0xf bank_mask:0xf
	v_pk_add_f32 v[136:137], v[136:137], v[152:153]
	s_nop 0
	v_mov_b32_e32 v153, v137
	v_mov_b32_e32 v152, v136
	s_nop 0
	v_mov_b32_dpp v153, v153 row_ror:8 row_mask:0xf bank_mask:0xf
	v_mov_b32_dpp v152, v152 row_ror:8 row_mask:0xf bank_mask:0xf
	v_pk_add_f32 v[136:137], v[136:137], v[152:153]
	v_or_b32_e32 v152, v65, v129
	v_pk_fma_f32 v[136:137], v[136:137], s[52:53], v[74:75] op_sel_hi:[1,0,0]
	v_ashrrev_i32_e32 v153, 31, v152
	v_mul_f32_e32 v135, 0x4b800000, v137
	v_cmp_gt_f32_e32 vcc, s65, v137
	s_nop 1
	v_cndmask_b32_e32 v135, v137, v135, vcc
	v_rsq_f32_e32 v135, v135
	s_nop 0
	v_mul_f32_e32 v65, 0x45800000, v135
	v_cndmask_b32_e32 v160, v135, v65, vcc
	v_mul_f32_e32 v65, 0x4b800000, v136
	v_cmp_gt_f32_e32 vcc, s65, v136
	v_pk_mul_f32 v[138:139], v[138:139], v[160:161] op_sel_hi:[1,0]
	v_pk_mul_f32 v[140:141], v[140:141], v[160:161] op_sel_hi:[1,0]
	v_cndmask_b32_e32 v65, v136, v65, vcc
	s_waitcnt vmcnt(0)
	v_pk_fma_f32 v[140:141], v[26:27], v[140:141], v[30:31]
	v_pk_fma_f32 v[138:139], v[24:25], v[138:139], v[28:29]
	v_rsq_f32_e32 v65, v65
	v_pk_fma_f32 v[138:139], v[142:143], v[156:157], v[138:139] op_sel_hi:[1,0,1]
	v_pk_fma_f32 v[140:141], v[144:145], v[156:157], v[140:141] op_sel_hi:[1,0,1]
	v_pk_mul_f32 v[138:139], v[138:139], v[154:155]
	v_pk_mul_f32 v[140:141], v[140:141], v[158:159]
	v_cvt_pk_bf16_f32 v136, v138, v139
	v_cvt_pk_bf16_f32 v137, v140, v141
	global_store_dwordx2 v[150:151], v[136:137], off
	v_mul_f32_e32 v135, 0x45800000, v65
	v_mad_u64_u32 v[136:137], s[56:57], v157, s63, v[66:67]
	v_cndmask_b32_e32 v140, v65, v135, vcc
	v_lshl_add_u32 v65, v157, 2, s64
	ds_read_b128 v[136:139], v136 offset:512
	ds_read_b32 v142, v65
	v_lshlrev_b32_e32 v150, 16, v134
	v_and_b32_e32 v151, 0xffff0000, v134
	v_pk_mul_f32 v[134:135], v[146:147], v[140:141] op_sel_hi:[1,0]
	v_pk_mul_f32 v[140:141], v[148:149], v[140:141] op_sel_hi:[1,0]
	v_pk_fma_f32 v[134:135], v[24:25], v[134:135], v[28:29]
	v_pk_fma_f32 v[140:141], v[26:27], v[140:141], v[30:31]
	v_lshlrev_b32_e32 v144, 16, v133
	v_and_b32_e32 v145, 0xffff0000, v133
	s_waitcnt lgkmcnt(0)
	v_pk_fma_f32 v[134:135], v[136:137], v[142:143], v[134:135] op_sel_hi:[1,0,1]
	v_pk_fma_f32 v[136:137], v[138:139], v[142:143], v[140:141] op_sel_hi:[1,0,1]
	v_pk_mul_f32 v[134:135], v[134:135], v[144:145]
	v_pk_mul_f32 v[136:137], v[136:137], v[150:151]
	v_cvt_pk_bf16_f32 v134, v134, v135
	v_cvt_pk_bf16_f32 v135, v136, v137
	v_lshlrev_b64 v[136:137], 12, v[152:153]
	v_lshl_add_u64 v[136:137], v[86:87], 0, v[136:137]
	global_store_dwordx2 v[136:137], v[134:135], off
	s_cmp_ge_u32 s71, s69
	s_cbranch_scc1 .LBB0_647
; #define UNPK(w) ((f32x4){bflo((w).x), bfhi((w).x), bflo((w).y), bfhi((w).y)})
; #define ROWSUM16(v) { v += dpp_f(v, 0); v += dpp_f(v, 1); v += dpp_f(v, 2); v += dpp_f(v, 3); }
; __device__ __forceinline__ void phase_scan(const Args& a, unsigned char* lds) {
;     ...
;                     for (int pp = 0; pp < 2; ++pp) { const int s = (2 * hw + pp) * 4 + hss;
;                         const f32x4 rc = UNPK(__builtin_bit_cast(u32x2, PFU(pp, 0))), kc = UNPK(__builtin_bit_cast(u32x2, PFU(pp, 1))), vc = UNPK(__builtin_bit_cast(u32x2, PFU(pp, 2)));
;                         const f32x4 rp = UNPK(__builtin_bit_cast(u32x2, PFU(pp, 3))), kp = UNPK(__builtin_bit_cast(u32x2, PFU(pp, 4))), vp = UNPK(__builtin_bit_cast(u32x2, PFU(pp, 5)));
;                         const h16x4 eh = __builtin_bit_cast(h16x4, PFU(pp, 6)), ah = __builtin_bit_cast(h16x4, PFU(pp, 7));
;                         const f32x4 r = rc + mu_r * (rp - rc), k = kc + mu_k * (kp - kc), v = vc + mu_v * (vp - vc);
;                         const f32x4 aa = {(float)ah[0], (float)ah[1], (float)ah[2], (float)ah[3]};
;                         const f32x4 dec = {__expf(-(float)eh[0]), __expf(-(float)eh[1]), __expf(-(float)eh[2]), __expf(-(float)eh[3])};
;                         const f32x4 kkr = k * kkw;
;                         float n2 = (kkr[0] * kkr[0] + kkr[1] * kkr[1]) + (kkr[2] * kkr[2] + kkr[3] * kkr[3]); ROWSUM16(n2)
;                         const f32x4 kk = kkr * rsqrtf(fmaxf(n2, 1e-24f));
;                         const f32x4 kpr = k * (1.f + (aa - 1.f) * kaw);
;                         const f32x4 bbv = kk * aa;
;                         const f32x4 bt = r * kpr * rkw;
;                         float bonus = (bt[0] + bt[1]) + (bt[2] + bt[3]); ROWSUM16(bonus)
;                         float* vs = vec + (size_t)((buf * 2 + hd) * 16 + s) * 384 + hc4;
;                         *(f32x4*)vs = r; *(f32x4*)(vs + 64) = kpr; *(f32x4*)(vs + 128) = v; *(f32x4*)(vs + 192) = dec; *(f32x4*)(vs + 256) = kk; *(f32x4*)(vs + 320) = bbv;
;                         if ((lane & 15) == 0) bon[(buf * 2 + hd) * 16 + s] = bonus;
.LBB0_642:
	s_lshl_b32 s56, s71, 1
	s_and_b32 s56, s56, 2
	s_waitcnt vmcnt(0)
	v_lshlrev_b32_e32 v134, 16, v108
	v_and_b32_e32 v135, 0xffff0000, v108
	v_lshlrev_b32_e32 v108, 16, v109
	v_and_b32_e32 v109, 0xffff0000, v109
	v_lshlrev_b32_e32 v140, 16, v113
	v_and_b32_e32 v141, 0xffff0000, v113
	v_add_u32_e32 v65, s56, v75
	v_lshlrev_b32_e32 v136, 16, v106
	v_and_b32_e32 v137, 0xffff0000, v106
	v_lshlrev_b32_e32 v142, 16, v116
	v_and_b32_e32 v116, 0xffff0000, v116
	v_lshlrev_b32_e32 v144, 16, v114
	v_and_b32_e32 v145, 0xffff0000, v114
	v_lshlrev_b32_e32 v146, 16, v115
	v_and_b32_e32 v147, 0xffff0000, v115
	v_sub_f32_e32 v115, v141, v109
	v_sub_f32_e32 v114, v140, v108
	v_lshl_or_b32 v133, v65, 4, v126
	v_lshlrev_b32_e32 v106, 16, v107
	v_lshlrev_b32_e32 v138, 16, v104
	v_and_b32_e32 v139, 0xffff0000, v104
	v_lshlrev_b32_e32 v65, 16, v112
	v_and_b32_e32 v112, 0xffff0000, v112
	v_lshlrev_b32_e32 v143, 16, v117
	v_pk_fma_f32 v[114:115], v[114:115], v[2:3], v[108:109]
	v_sub_f32_e32 v109, v116, v137
	v_sub_f32_e32 v108, v142, v136
	v_sub_f32_e32 v113, v112, v135
	v_sub_f32_e32 v112, v65, v134
	v_sub_f32_e32 v116, v143, v106
	v_pk_fma_f32 v[142:143], v[108:109], v[4:5], v[136:137]
	v_sub_f32_e32 v109, v145, v139
	v_sub_f32_e32 v108, v144, v138
	v_cvt_f32_f16_e32 v65, v110
	v_pk_fma_f32 v[112:113], v[112:113], v[0:1], v[134:135]
	v_pk_fma_f32 v[134:135], v[108:109], v[8:9], v[138:139]
	v_cvt_f32_f16_sdwa v109, v110 dst_sel:DWORD dst_unused:UNUSED_PAD src0_sel:WORD_1
	v_and_b32_e32 v107, 0xffff0000, v107
	v_and_b32_e32 v117, 0xffff0000, v117
	v_cvt_f32_f16_e32 v110, v111
	v_lshlrev_b32_e32 v104, 16, v105
	v_and_b32_e32 v105, 0xffff0000, v105
	v_sub_f32_e32 v117, v117, v107
	v_pk_fma_f32 v[106:107], v[116:117], v[6:7], v[106:107]
	v_sub_f32_e32 v117, v147, v105
	v_sub_f32_e32 v116, v146, v104
	v_mul_f32_e32 v65, 0xbfb8aa3b, v65
	v_pk_fma_f32 v[136:137], v[116:117], v[10:11], v[104:105]
	v_cvt_f32_f16_sdwa v105, v118 dst_sel:DWORD dst_unused:UNUSED_PAD src0_sel:WORD_1
	v_cvt_f32_f16_e32 v104, v118
	v_cvt_f32_f16_sdwa v145, v119 dst_sel:DWORD dst_unused:UNUSED_PAD src0_sel:WORD_1
	v_cvt_f32_f16_e32 v144, v119
	v_exp_f32_e32 v108, v65
	v_mul_f32_e32 v65, 0xbfb8aa3b, v109
	v_pk_mul_f32 v[116:117], v[12:13], v[142:143]
	v_pk_mul_f32 v[118:119], v[14:15], v[106:107]
	v_exp_f32_e32 v109, v65
	v_mul_f32_e32 v65, 0xbfb8aa3b, v110
	v_cvt_f32_f16_sdwa v146, v111 dst_sel:DWORD dst_unused:UNUSED_PAD src0_sel:WORD_1
	v_pk_mul_f32 v[110:111], v[118:119], v[118:119]
	v_pk_mul_f32 v[138:139], v[116:117], v[116:117]
	s_nop 0
	v_pk_mov_b32 v[140:141], v[138:139], v[110:111] op_sel:[1,0]
	v_mov_b32_e32 v139, v111
	v_pk_add_f32 v[110:111], v[140:141], v[138:139]
	v_pk_add_f32 v[140:141], v[104:105], -1.0 op_sel_hi:[1,0]
	v_add_f32_e32 v110, v110, v111
	s_nop 1
	v_add_f32_dpp v110, v110, v110 quad_perm:[1,0,3,2] row_mask:0xf bank_mask:0xf
	s_nop 1
	v_add_f32_dpp v110, v110, v110 quad_perm:[2,3,0,1] row_mask:0xf bank_mask:0xf
	s_nop 1
	v_add_f32_dpp v110, v110, v110 row_ror:4 row_mask:0xf bank_mask:0xf
	s_nop 1
	v_add_f32_dpp v110, v110, v110 row_ror:8 row_mask:0xf bank_mask:0xf
	v_max_f32_e32 v110, 0x179abe15, v110
	v_rsq_f32_e32 v138, v110
	v_exp_f32_e32 v110, v65
	v_mul_f32_e32 v65, 0xbfb8aa3b, v146
	v_pk_fma_f32 v[146:147], v[140:141], v[16:17], 1.0 op_sel_hi:[1,1,0]
	v_pk_mul_f32 v[118:119], v[118:119], v[138:139] op_sel_hi:[1,0]
	v_pk_mul_f32 v[116:117], v[116:117], v[138:139] op_sel_hi:[1,0]
	v_pk_add_f32 v[138:139], v[144:145], -1.0 op_sel_hi:[1,0]
	v_exp_f32_e32 v111, v65
	v_pk_fma_f32 v[138:139], v[138:139], v[18:19], 1.0 op_sel_hi:[1,1,0]
	v_pk_mul_f32 v[144:145], v[144:145], v[118:119]
	v_pk_mul_f32 v[140:141], v[138:139], v[106:107]
	v_pk_mul_f32 v[138:139], v[146:147], v[142:143]
	v_pk_mul_f32 v[142:143], v[104:105], v[116:117]
	v_pk_mul_f32 v[104:105], v[138:139], v[112:113]
	v_pk_mul_f32 v[106:107], v[140:141], v[114:115]
	v_pk_mul_f32 v[104:105], v[20:21], v[104:105]
	v_pk_mul_f32 v[106:107], v[22:23], v[106:107]
	v_add_f32_e32 v65, v104, v105
	v_add_f32_e32 v104, v106, v107
	v_add_f32_e32 v65, v65, v104
	s_nop 1
	v_add_f32_dpp v65, v65, v65 quad_perm:[1,0,3,2] row_mask:0xf bank_mask:0xf
	s_nop 1
	v_add_f32_dpp v65, v65, v65 quad_perm:[2,3,0,1] row_mask:0xf bank_mask:0xf
	v_mov_b32_e32 v104, v65
	s_nop 1
	v_mov_b32_dpp v104, v104 row_ror:4 row_mask:0xf bank_mask:0xf
	v_add_f32_e32 v105, v65, v104
	v_mov_b32_e32 v106, v105
	v_mul_lo_u32 v65, v133, s63
	v_add_u32_e32 v65, v66, v65
	v_mov_b32_dpp v106, v106 row_ror:8 row_mask:0xf bank_mask:0xf
	v_lshl_add_u32 v104, v133, 2, 0
	ds_write_b128 v65, v[112:115]
	ds_write_b128 v65, v[138:141] offset:256
	ds_write_b128 v65, v[134:137] offset:512
	ds_write_b128 v65, v[108:111] offset:768
	ds_write_b128 v65, v[116:119] offset:1024
	ds_write_b128 v65, v[142:145] offset:1280
; #define UNPK(w) ((f32x4){bflo((w).x), bfhi((w).x), bflo((w).y), bfhi((w).y)})
; #define ROWSUM16(v) { v += dpp_f(v, 0); v += dpp_f(v, 1); v += dpp_f(v, 2); v += dpp_f(v, 3); }
; __device__ __forceinline__ void phase_scan(const Args& a, unsigned char* lds) {
;     ...
;                     for (int pp = 0; pp < 2; ++pp) { const int s = (2 * hw + pp) * 4 + hss;
;                         const f32x4 rc = UNPK(__builtin_bit_cast(u32x2, PFU(pp, 0))), kc = UNPK(__builtin_bit_cast(u32x2, PFU(pp, 1))), vc = UNPK(__builtin_bit_cast(u32x2, PFU(pp, 2)));
;                         const f32x4 rp = UNPK(__builtin_bit_cast(u32x2, PFU(pp, 3))), kp = UNPK(__builtin_bit_cast(u32x2, PFU(pp, 4))), vp = UNPK(__builtin_bit_cast(u32x2, PFU(pp, 5)));
;                         const h16x4 eh = __builtin_bit_cast(h16x4, PFU(pp, 6)), ah = __builtin_bit_cast(h16x4, PFU(pp, 7));
;                         const f32x4 r = rc + mu_r * (rp - rc), k = kc + mu_k * (kp - kc), v = vc + mu_v * (vp - vc);
;                         const f32x4 aa = {(float)ah[0], (float)ah[1], (float)ah[2], (float)ah[3]};
;                         const f32x4 dec = {__expf(-(float)eh[0]), __expf(-(float)eh[1]), __expf(-(float)eh[2]), __expf(-(float)eh[3])};
;                         const f32x4 kkr = k * kkw;
;                         float n2 = (kkr[0] * kkr[0] + kkr[1] * kkr[1]) + (kkr[2] * kkr[2] + kkr[3] * kkr[3]); ROWSUM16(n2)
;                         const f32x4 kk = kkr * rsqrtf(fmaxf(n2, 1e-24f));
;                         const f32x4 kpr = k * (1.f + (aa - 1.f) * kaw);
;                         const f32x4 bbv = kk * aa;
;                         const f32x4 bt = r * kpr * rkw;
;                         float bonus = (bt[0] + bt[1]) + (bt[2] + bt[3]); ROWSUM16(bonus)
;                         float* vs = vec + (size_t)((buf * 2 + hd) * 16 + s) * 384 + hc4;
;                         *(f32x4*)vs = r; *(f32x4*)(vs + 64) = kpr; *(f32x4*)(vs + 128) = v; *(f32x4*)(vs + 192) = dec; *(f32x4*)(vs + 256) = kk; *(f32x4*)(vs + 320) = bbv;
;                         if ((lane & 15) == 0) bon[(buf * 2 + hd) * 16 + s] = bonus;
;                     }
	s_and_saveexec_b64 s[56:57], s[8:9]
	v_add_f32_e32 v105, v105, v106
	v_add_u32_e32 v106, 0x1c000, v104
	ds_write_b32 v106, v105
	s_or_b64 exec, exec, s[56:57]
	v_lshlrev_b32_e32 v106, 16, v98
	v_and_b32_e32 v107, 0xffff0000, v98
	v_lshlrev_b32_e32 v98, 16, v99
	v_and_b32_e32 v99, 0xffff0000, v99
	v_lshlrev_b32_e32 v108, 16, v94
	v_and_b32_e32 v109, 0xffff0000, v94
	v_lshlrev_b32_e32 v110, 16, v95
	v_and_b32_e32 v111, 0xffff0000, v95
	v_lshlrev_b32_e32 v94, 16, v102
	v_and_b32_e32 v95, 0xffff0000, v102
	v_lshlrev_b32_e32 v102, 16, v103
	v_and_b32_e32 v103, 0xffff0000, v103
	v_lshlrev_b32_e32 v105, 16, v100
	v_and_b32_e32 v100, 0xffff0000, v100
	v_lshlrev_b32_e32 v116, 16, v92
	v_and_b32_e32 v117, 0xffff0000, v92
	v_lshlrev_b32_e32 v118, 16, v93
	v_and_b32_e32 v119, 0xffff0000, v93
	v_sub_f32_e32 v93, v95, v107
	v_sub_f32_e32 v92, v94, v106
	v_sub_f32_e32 v95, v103, v99
	v_sub_f32_e32 v94, v102, v98
	v_lshlrev_b32_e32 v112, 16, v96
	v_and_b32_e32 v113, 0xffff0000, v96
	v_lshlrev_b32_e32 v96, 16, v97
	v_and_b32_e32 v97, 0xffff0000, v97
	v_lshlrev_b32_e32 v114, 16, v101
	v_and_b32_e32 v101, 0xffff0000, v101
	v_pk_fma_f32 v[94:95], v[2:3], v[94:95], v[98:99]
	v_sub_f32_e32 v99, v100, v109
	v_sub_f32_e32 v98, v105, v108
	v_sub_f32_e32 v101, v101, v111
	v_sub_f32_e32 v100, v114, v110
	v_pk_fma_f32 v[114:115], v[4:5], v[98:99], v[108:109]
	v_sub_f32_e32 v99, v119, v97
	v_sub_f32_e32 v98, v118, v96
	v_cvt_f32_f16_sdwa v119, v90 dst_sel:DWORD dst_unused:UNUSED_PAD src0_sel:WORD_1
	v_cvt_f32_f16_e32 v118, v90
	v_cvt_f32_f16_e32 v90, v88
	v_cvt_f32_f16_sdwa v88, v88 dst_sel:DWORD dst_unused:UNUSED_PAD src0_sel:WORD_1
	v_pk_fma_f32 v[110:111], v[6:7], v[100:101], v[110:111]
	v_sub_f32_e32 v101, v117, v113
	v_sub_f32_e32 v100, v116, v112
	v_cvt_f32_f16_sdwa v117, v91 dst_sel:DWORD dst_unused:UNUSED_PAD src0_sel:WORD_1
	v_cvt_f32_f16_e32 v116, v91
	v_cvt_f32_f16_e32 v91, v89
	v_mul_f32_e32 v90, 0xbfb8aa3b, v90
	v_mul_f32_e32 v88, 0xbfb8aa3b, v88
	v_pk_fma_f32 v[98:99], v[10:11], v[98:99], v[96:97]
	v_pk_fma_f32 v[96:97], v[8:9], v[100:101], v[112:113]
	v_exp_f32_e32 v100, v90
	v_exp_f32_e32 v101, v88
	v_mul_f32_e32 v105, 0xbfb8aa3b, v91
	v_cvt_f32_f16_sdwa v112, v89 dst_sel:DWORD dst_unused:UNUSED_PAD src0_sel:WORD_1
	v_pk_mul_f32 v[88:89], v[12:13], v[114:115]
	v_pk_mul_f32 v[90:91], v[14:15], v[110:111]
	v_pk_fma_f32 v[92:93], v[0:1], v[92:93], v[106:107]
	v_pk_mul_f32 v[102:103], v[90:91], v[90:91]
	v_pk_mul_f32 v[106:107], v[88:89], v[88:89]
	s_nop 0
	v_pk_mov_b32 v[108:109], v[106:107], v[102:103] op_sel:[1,0]
	v_mov_b32_e32 v107, v103
	v_pk_add_f32 v[102:103], v[108:109], v[106:107]
	s_nop 0
	v_add_f32_e32 v102, v102, v103
	s_nop 1
	v_add_f32_dpp v102, v102, v102 quad_perm:[1,0,3,2] row_mask:0xf bank_mask:0xf
	s_nop 1
	v_add_f32_dpp v102, v102, v102 quad_perm:[2,3,0,1] row_mask:0xf bank_mask:0xf
	s_nop 1
	v_add_f32_dpp v102, v102, v102 row_ror:4 row_mask:0xf bank_mask:0xf
	s_nop 1
	v_add_f32_dpp v102, v102, v102 row_ror:8 row_mask:0xf bank_mask:0xf
	v_max_f32_e32 v102, 0x179abe15, v102
	v_rsq_f32_e32 v106, v102
	v_mul_f32_e32 v103, 0xbfb8aa3b, v112
	v_exp_f32_e32 v102, v105
	v_exp_f32_e32 v103, v103
	v_pk_mul_f32 v[108:109], v[90:91], v[106:107] op_sel_hi:[1,0]
	v_pk_mul_f32 v[106:107], v[88:89], v[106:107] op_sel_hi:[1,0]
	v_pk_add_f32 v[88:89], v[118:119], -1.0 op_sel_hi:[1,0]
	v_pk_add_f32 v[90:91], v[116:117], -1.0 op_sel_hi:[1,0]
	v_pk_fma_f32 v[88:89], v[16:17], v[88:89], 1.0 op_sel_hi:[1,1,0]
	v_pk_fma_f32 v[90:91], v[18:19], v[90:91], 1.0 op_sel_hi:[1,1,0]
	v_pk_mul_f32 v[116:117], v[116:117], v[108:109]
	v_pk_mul_f32 v[112:113], v[110:111], v[90:91]
	v_pk_mul_f32 v[110:111], v[114:115], v[88:89]
	v_pk_mul_f32 v[90:91], v[94:95], v[112:113]
	v_pk_mul_f32 v[88:89], v[92:93], v[110:111]
	v_pk_mul_f32 v[90:91], v[22:23], v[90:91]
	v_pk_mul_f32 v[88:89], v[20:21], v[88:89]
	v_pk_mul_f32 v[114:115], v[118:119], v[106:107]
	v_add_f32_e32 v88, v88, v89
	v_add_f32_e32 v89, v90, v91
	v_add_f32_e32 v88, v88, v89
	v_mov_b32_e32 v89, v88
	ds_write_b128 v65, v[92:95] offset:6144
	ds_write_b128 v65, v[110:113] offset:6400
	ds_write_b128 v65, v[96:99] offset:6656
	ds_write_b128 v65, v[100:103] offset:6912
	ds_write_b128 v65, v[106:109] offset:7168
	ds_write_b128 v65, v[114:117] offset:7424
	v_mov_b32_dpp v89, v89 quad_perm:[1,0,3,2] row_mask:0xf bank_mask:0xf
	v_add_f32_e32 v88, v88, v89
	s_nop 1
	v_add_f32_dpp v88, v88, v88 quad_perm:[2,3,0,1] row_mask:0xf bank_mask:0xf
	s_nop 1
	v_add_f32_dpp v88, v88, v88 row_ror:4 row_mask:0xf bank_mask:0xf
	v_mov_b32_e32 v89, v88
	s_nop 1
	v_mov_b32_dpp v89, v89 row_ror:8 row_mask:0xf bank_mask:0xf
	s_and_saveexec_b64 s[56:57], s[8:9]
	v_add_f32_e32 v65, v88, v89
	v_add_u32_e32 v88, 0x1c010, v104
	ds_write_b32 v88, v65
	s_or_b64 exec, exec, s[56:57]

; template <int NS>
; __device__ __forceinline__ void attn_unit(const AUnit& u, unsigned char* lds, const bf16_t* __restrict__ GT, bf16_t* BRc, float sc, float lam, const float* __restrict__ subln) {
;     ...
;     const int qrow = u.qrow0 + wid * 32 + l31;
;     unsigned char* qs = lds + 2 * A_BUF + wid * (32 * A_KRS);
;     if (active) {
;         const bf16_t* qp = BRc + (size_t)qrow * BR + u.qcol + hh * 64;
; #pragma unroll
;         for (int i = 0; i < 8; ++i) *(u32x4*)(qs + l31 * A_KRS + hh * 128 + i * 16) = *(const u32x4*)(qp + i * 8);
;     }
;     const unsigned char* q_rd = qs + l31 * A_KRS + hh * 16;
;     f32x16 O0[4], O1[4];
;     float m0 = -1e30f, m1 = -1e30f, l0r = 0.f, l1r = 0.f;
; #pragma unroll
;     for (int d = 0; d < 4; ++d)
; #pragma unroll
;         for (int r = 0; r < 16; ++r) { O0[d][r] = 0.f; O1[d][r] = 0.f; }
;     u32x4 rk[2], rv[2];
;     attn_load1(u.kb, u.ld, 0, rk); attn_load1(u.vb, u.ld, 0, rv);
;     attn_store1(lds, A_KRS, rk); attn_store1(lds + A_KT, A_VRS, rv);
;     __syncthreads();
.LBB0_1157:
	v_lshl_add_u64 v[196:197], s[10:11], 0, v[180:181]
	v_mov_b32_e32 v191, v181
	v_lshl_add_u64 v[0:1], v[196:197], 0, v[190:191]
	v_mov_b32_e32 v193, v181
	v_lshl_add_u64 v[198:199], s[8:9], 0, v[180:181]
	v_lshl_add_u64 v[2:3], v[196:197], 0, v[192:193]
	global_load_dwordx4 v[160:163], v[0:1], off
	global_load_dwordx4 v[164:167], v[2:3], off
	v_lshl_add_u64 v[0:1], v[198:199], 0, v[190:191]
	v_lshl_add_u64 v[2:3], v[198:199], 0, v[192:193]
	global_load_dwordx4 v[128:131], v[0:1], off
	global_load_dwordx4 v[132:135], v[2:3], off
	v_add_u32_e32 v194, s13, v209
	v_cmp_gt_u32_e64 s[6:7], s6, v179
	v_ashrrev_i32_e32 v195, 31, v194
	s_and_saveexec_b64 s[12:13], s[6:7]
	s_cbranch_execz .LBB0_1159
	v_lshlrev_b64 v[0:1], 12, v[194:195]
	v_lshl_add_u64 v[0:1], s[52:53], 0, v[0:1]
	s_ashr_i32 s61, s60, 31
	v_lshl_add_u64 v[0:1], s[60:61], 1, v[0:1]
	v_mov_b32_e32 v189, v181
	v_lshl_add_u64 v[32:33], v[0:1], 0, v[188:189]
	global_load_dwordx4 v[0:3], v[32:33], off
	global_load_dwordx4 v[4:7], v[32:33], off offset:16
	global_load_dwordx4 v[8:11], v[32:33], off offset:32
	global_load_dwordx4 v[12:15], v[32:33], off offset:48
	global_load_dwordx4 v[16:19], v[32:33], off offset:64
	global_load_dwordx4 v[20:23], v[32:33], off offset:80
	global_load_dwordx4 v[24:27], v[32:33], off offset:96
	global_load_dwordx4 v[28:31], v[32:33], off offset:112
	s_waitcnt vmcnt(7)
	ds_write_b128 v220, v[0:3]
	s_waitcnt vmcnt(6)
	ds_write_b128 v220, v[4:7] offset:16
	s_waitcnt vmcnt(5)
	ds_write_b128 v220, v[8:11] offset:32
	s_waitcnt vmcnt(4)
	ds_write_b128 v220, v[12:15] offset:48
	s_waitcnt vmcnt(3)
	ds_write_b128 v220, v[16:19] offset:64
	s_waitcnt vmcnt(2)
	ds_write_b128 v220, v[20:23] offset:80
	s_waitcnt vmcnt(1)
	ds_write_b128 v220, v[24:27] offset:96
	s_waitcnt vmcnt(0)
	ds_write_b128 v220, v[28:31] offset:112
.LBB0_1159:
	s_or_b64 exec, exec, s[12:13]
	v_add_u32_e32 v16, s14, v208
	v_mov_b32_e32 v17, s77
	v_sub_u32_e32 v18, s15, v217
	v_mov_b32_e32 v14, v181
	v_mov_b32_e32 v15, v181
	v_mov_b32_e32 v0, v181
	v_mov_b32_e32 v1, v181
	v_mov_b32_e32 v2, v181
	v_mov_b32_e32 v3, v181
	v_mov_b32_e32 v4, v181
	v_mov_b32_e32 v5, v181
	v_mov_b32_e32 v6, v181
	v_mov_b32_e32 v7, v181
	v_mov_b32_e32 v8, v181
	v_mov_b32_e32 v9, v181
	v_mov_b32_e32 v10, v181
	v_mov_b32_e32 v11, v181
	v_mov_b32_e32 v12, v181
	v_mov_b32_e32 v13, v181
	v_cndmask_b32_e64 v193, v16, v17, s[4:5]
	v_cmp_lt_u32_e64 s[8:9], 32, v18
	v_cmp_lt_u32_e64 s[10:11], 33, v18
	v_cmp_lt_u32_e64 s[12:13], 34, v18
	v_cmp_lt_u32_e64 s[14:15], 35, v18
	v_cmp_lt_u32_e64 s[16:17], 40, v18
	v_cmp_lt_u32_e64 s[18:19], 41, v18
	v_cmp_lt_u32_e64 s[20:21], 42, v18
	v_cmp_lt_u32_e64 s[22:23], 43, v18
	v_cmp_lt_u32_e64 s[24:25], 48, v18
	v_cmp_lt_u32_e64 s[26:27], 49, v18
	v_cmp_lt_u32_e64 s[28:29], 50, v18
	v_cmp_lt_u32_e64 s[30:31], 51, v18
	v_cmp_lt_u32_e64 s[34:35], 56, v18
	v_cmp_lt_u32_e64 s[36:37], 57, v18
	v_cmp_lt_u32_e64 s[38:39], 58, v18
	v_cmp_lt_u32_e64 s[40:41], 59, v18
	v_mov_b64_e32 v[46:47], v[14:15]
	v_mov_b64_e32 v[62:63], v[14:15]
	v_mov_b64_e32 v[78:79], v[14:15]
	v_mov_b64_e32 v[30:31], v[14:15]
	v_mov_b64_e32 v[94:95], v[14:15]
	v_mov_b64_e32 v[110:111], v[14:15]
	v_mov_b64_e32 v[126:127], v[14:15]
	v_add_u32_e32 v136, v212, v213
	s_add_i32 s61, s77, -1
	s_mov_b32 s42, 0
	v_mov_b32_e32 v228, 0xf149f2ca
	v_mov_b32_e32 v226, 0
	v_mov_b32_e32 v189, v177
	v_mov_b32_e32 v191, v175
	v_mov_b32_e32 v227, 0
	v_mov_b64_e32 v[44:45], v[12:13]
	v_mov_b64_e32 v[42:43], v[10:11]
	v_mov_b64_e32 v[40:41], v[8:9]
	v_mov_b64_e32 v[38:39], v[6:7]
	v_mov_b64_e32 v[36:37], v[4:5]
	v_mov_b64_e32 v[34:35], v[2:3]
	v_mov_b64_e32 v[32:33], v[0:1]
	v_mov_b64_e32 v[60:61], v[12:13]
	v_mov_b64_e32 v[58:59], v[10:11]
	v_mov_b64_e32 v[56:57], v[8:9]
	v_mov_b64_e32 v[54:55], v[6:7]
	v_mov_b64_e32 v[52:53], v[4:5]
	v_mov_b64_e32 v[50:51], v[2:3]
	v_mov_b64_e32 v[48:49], v[0:1]
	v_mov_b64_e32 v[76:77], v[12:13]
	v_mov_b64_e32 v[74:75], v[10:11]
	v_mov_b64_e32 v[72:73], v[8:9]
	v_mov_b64_e32 v[70:71], v[6:7]
	v_mov_b64_e32 v[68:69], v[4:5]
	v_mov_b64_e32 v[66:67], v[2:3]
	v_mov_b64_e32 v[64:65], v[0:1]
	v_mov_b64_e32 v[28:29], v[12:13]
	v_mov_b64_e32 v[26:27], v[10:11]
	v_mov_b64_e32 v[24:25], v[8:9]
	v_mov_b64_e32 v[22:23], v[6:7]
	v_mov_b64_e32 v[20:21], v[4:5]
	v_mov_b64_e32 v[18:19], v[2:3]
	v_mov_b64_e32 v[16:17], v[0:1]
	v_mov_b64_e32 v[92:93], v[12:13]
	v_mov_b64_e32 v[90:91], v[10:11]
	v_mov_b64_e32 v[88:89], v[8:9]
	v_mov_b64_e32 v[86:87], v[6:7]
	v_mov_b64_e32 v[84:85], v[4:5]
	v_mov_b64_e32 v[82:83], v[2:3]
	v_mov_b64_e32 v[80:81], v[0:1]
	v_mov_b64_e32 v[108:109], v[12:13]
	v_mov_b64_e32 v[106:107], v[10:11]
	v_mov_b64_e32 v[104:105], v[8:9]
	v_mov_b64_e32 v[102:103], v[6:7]
	v_mov_b64_e32 v[100:101], v[4:5]
	v_mov_b64_e32 v[98:99], v[2:3]
	v_mov_b64_e32 v[96:97], v[0:1]
	v_mov_b64_e32 v[124:125], v[12:13]
	v_mov_b64_e32 v[122:123], v[10:11]
	v_mov_b64_e32 v[120:121], v[8:9]
	v_mov_b64_e32 v[118:119], v[6:7]
	v_mov_b64_e32 v[116:117], v[4:5]
	v_mov_b64_e32 v[114:115], v[2:3]
	v_mov_b64_e32 v[112:113], v[0:1]
	v_mov_b32_e32 v229, 0xf149f2ca
	v_add_u32_e32 v137, v212, v214
	v_add_u32_e32 v138, v212, v215
	v_add_u32_e32 v139, v212, v216
	s_waitcnt vmcnt(3)
	ds_write_b128 v136, v[160:163]
	s_waitcnt vmcnt(2)
	ds_write_b128 v137, v[164:167]
	s_waitcnt vmcnt(1)
	ds_write_b128 v138, v[128:131] offset:17408
	s_waitcnt vmcnt(0)
	ds_write_b128 v139, v[132:135] offset:17408
	s_waitcnt lgkmcnt(0)
	s_barrier

; template <int NS, int SI>
; __device__ __forceinline__ void attn_stream(const unsigned char* kbase, const unsigned char* vbase, const unsigned char* q_rd, bool mask_tail, int last_valid, int hh, float sc,
;                                             f32x16 (&O)[4], float& mrun, float& lrun) {
;     ...
;     float mx = __builtin_amdgcn_fmed3f(S0[0], S1[0], __builtin_inff());
; #pragma unroll
;     for (int r = 1; r < 16; ++r) { mx = __builtin_amdgcn_fmed3f(mx, S0[r], __builtin_inff()); mx = __builtin_amdgcn_fmed3f(mx, S1[r], __builtin_inff()); }
;     mx = fmaxf(mx, __shfl_xor(mx, 32));
;     const float mn = fmaxf(mrun, mx * sc);
;     const float alpha = __builtin_amdgcn_exp2f(mrun - mn);
;     mrun = mn;
;     f32x2 ls2 = {0.f, 0.f};
;     const f32x2 sc2 = {sc, sc}, mn2 = {mn, mn};
; #pragma unroll
;     for (int r = 0; r < 16; r += 2) {
;         const f32x2 t0 = (f32x2){S0[r], S0[r + 1]} * sc2 - mn2, t1 = (f32x2){S1[r], S1[r + 1]} * sc2 - mn2;
;         const f32x2 p0 = {__builtin_amdgcn_exp2f(t0.x), __builtin_amdgcn_exp2f(t0.y)}, p1 = {__builtin_amdgcn_exp2f(t1.x), __builtin_amdgcn_exp2f(t1.y)};
;         S0[r] = p0.x; S0[r + 1] = p0.y; S1[r] = p1.x; S1[r + 1] = p1.y; ls2 += p0 + p1;
;     }
;     lrun = lrun * alpha + (ls2.x + ls2.y);
;     if (__any(alpha != 1.0f)) {
; #pragma unroll
;         for (int d = 0; d < 4; ++d) O[d] = O[d] * alpha;
.LBB0_1165:
	s_nop 9
	v_max3_f32 v200, v128, v129, v130
	v_max3_f32 v202, v144, v145, v146
	v_max3_f32 v200, v200, v131, v132
	v_max3_f32 v202, v202, v147, v148
	v_max3_f32 v200, v200, v133, v134
	v_max3_f32 v202, v202, v149, v150
	v_max3_f32 v200, v200, v135, v136
	v_max3_f32 v202, v202, v151, v152
	v_max3_f32 v200, v200, v137, v138
	v_max3_f32 v202, v202, v153, v154
	v_max3_f32 v200, v200, v139, v140
	v_max3_f32 v202, v202, v155, v156
	v_max3_f32 v200, v200, v141, v142
	v_max3_f32 v202, v202, v157, v158
	v_max3_f32 v200, v200, v143, v159
	v_max_f32_e32 v200, v200, v202
	v_mov_b32_e32 v202, v200
	s_nop 1
	v_permlane32_swap_b32_e32 v202, v200
	v_max_f32_e32 v200, v200, v202
	v_mul_f32_e32 v200, 0x3e38aa3b, v200
	v_max_f32_e32 v200, v228, v200
	v_sub_f32_e32 v202, v200, v228
	v_cmp_lt_f32_e32 vcc, 4.0, v202
	s_nop 1
	v_cndmask_b32_e32 v200, v228, v200, vcc
	v_cmp_neq_f32_e32 vcc, v228, v200
	v_mov_b32_e32 v202, 1.0
	s_cbranch_vccz .LBB0_1167
	v_sub_f32_e32 v202, v228, v200
	v_exp_f32_e32 v202, v202
	s_nop 0
	v_pk_mul_f32 v[78:79], v[78:79], v[202:203] op_sel_hi:[1,0]
	v_pk_mul_f32 v[76:77], v[76:77], v[202:203] op_sel_hi:[1,0]
	v_pk_mul_f32 v[74:75], v[74:75], v[202:203] op_sel_hi:[1,0]
	v_pk_mul_f32 v[72:73], v[72:73], v[202:203] op_sel_hi:[1,0]
	v_pk_mul_f32 v[70:71], v[70:71], v[202:203] op_sel_hi:[1,0]
	v_pk_mul_f32 v[68:69], v[68:69], v[202:203] op_sel_hi:[1,0]
	v_pk_mul_f32 v[66:67], v[66:67], v[202:203] op_sel_hi:[1,0]
	v_pk_mul_f32 v[64:65], v[64:65], v[202:203] op_sel_hi:[1,0]
	v_pk_mul_f32 v[62:63], v[62:63], v[202:203] op_sel_hi:[1,0]
	v_pk_mul_f32 v[60:61], v[60:61], v[202:203] op_sel_hi:[1,0]
	v_pk_mul_f32 v[58:59], v[58:59], v[202:203] op_sel_hi:[1,0]
	v_pk_mul_f32 v[56:57], v[56:57], v[202:203] op_sel_hi:[1,0]
	v_pk_mul_f32 v[54:55], v[54:55], v[202:203] op_sel_hi:[1,0]
	v_pk_mul_f32 v[52:53], v[52:53], v[202:203] op_sel_hi:[1,0]
	v_pk_mul_f32 v[50:51], v[50:51], v[202:203] op_sel_hi:[1,0]
	v_pk_mul_f32 v[48:49], v[48:49], v[202:203] op_sel_hi:[1,0]
	v_pk_mul_f32 v[46:47], v[46:47], v[202:203] op_sel_hi:[1,0]
	v_pk_mul_f32 v[44:45], v[44:45], v[202:203] op_sel_hi:[1,0]
	v_pk_mul_f32 v[42:43], v[42:43], v[202:203] op_sel_hi:[1,0]
	v_pk_mul_f32 v[40:41], v[40:41], v[202:203] op_sel_hi:[1,0]
	v_pk_mul_f32 v[38:39], v[38:39], v[202:203] op_sel_hi:[1,0]
	v_pk_mul_f32 v[36:37], v[36:37], v[202:203] op_sel_hi:[1,0]
	v_pk_mul_f32 v[34:35], v[34:35], v[202:203] op_sel_hi:[1,0]
	v_pk_mul_f32 v[32:33], v[32:33], v[202:203] op_sel_hi:[1,0]
	v_pk_mul_f32 v[14:15], v[14:15], v[202:203] op_sel_hi:[1,0]
	v_pk_mul_f32 v[12:13], v[12:13], v[202:203] op_sel_hi:[1,0]
	v_pk_mul_f32 v[10:11], v[10:11], v[202:203] op_sel_hi:[1,0]
	v_pk_mul_f32 v[8:9], v[8:9], v[202:203] op_sel_hi:[1,0]
	v_pk_mul_f32 v[6:7], v[6:7], v[202:203] op_sel_hi:[1,0]
	v_pk_mul_f32 v[4:5], v[4:5], v[202:203] op_sel_hi:[1,0]
	v_pk_mul_f32 v[2:3], v[2:3], v[202:203] op_sel_hi:[1,0]
	v_pk_mul_f32 v[0:1], v[0:1], v[202:203] op_sel_hi:[1,0]
.LBB0_1167:
	v_pk_fma_f32 v[128:129], v[128:129], s[58:59], v[200:201] op_sel_hi:[1,0,0] neg_lo:[0,0,1] neg_hi:[0,0,1]
	v_pk_fma_f32 v[144:145], v[144:145], s[58:59], v[200:201] op_sel_hi:[1,0,0] neg_lo:[0,0,1] neg_hi:[0,0,1]
	v_exp_f32_e32 v232, v128
	v_exp_f32_e32 v233, v129
	v_exp_f32_e32 v144, v144
	v_exp_f32_e32 v145, v145
	v_pk_fma_f32 v[128:129], v[130:131], s[58:59], v[200:201] op_sel_hi:[1,0,0] neg_lo:[0,0,1] neg_hi:[0,0,1]
	v_pk_fma_f32 v[130:131], v[146:147], s[58:59], v[200:201] op_sel_hi:[1,0,0] neg_lo:[0,0,1] neg_hi:[0,0,1]
	v_exp_f32_e32 v146, v128
	v_exp_f32_e32 v147, v129
	v_exp_f32_e32 v234, v130
	v_exp_f32_e32 v235, v131
	v_pk_fma_f32 v[132:133], v[132:133], s[58:59], v[200:201] op_sel_hi:[1,0,0] neg_lo:[0,0,1] neg_hi:[0,0,1]
	v_pk_fma_f32 v[148:149], v[148:149], s[58:59], v[200:201] op_sel_hi:[1,0,0] neg_lo:[0,0,1] neg_hi:[0,0,1]
	v_exp_f32_e32 v236, v132
	v_exp_f32_e32 v237, v133
	v_exp_f32_e32 v148, v148
	v_exp_f32_e32 v149, v149
	v_pk_fma_f32 v[132:133], v[134:135], s[58:59], v[200:201] op_sel_hi:[1,0,0] neg_lo:[0,0,1] neg_hi:[0,0,1]
	v_pk_fma_f32 v[134:135], v[150:151], s[58:59], v[200:201] op_sel_hi:[1,0,0] neg_lo:[0,0,1] neg_hi:[0,0,1]
	v_exp_f32_e32 v150, v132
	v_exp_f32_e32 v151, v133
	v_exp_f32_e32 v238, v134
	v_exp_f32_e32 v239, v135
	v_pk_fma_f32 v[132:133], v[136:137], s[58:59], v[200:201] op_sel_hi:[1,0,0] neg_lo:[0,0,1] neg_hi:[0,0,1]
	v_pk_fma_f32 v[134:135], v[152:153], s[58:59], v[200:201] op_sel_hi:[1,0,0] neg_lo:[0,0,1] neg_hi:[0,0,1]
	v_pk_add_f32 v[128:129], v[144:145], v[232:233]
	v_exp_f32_e32 v152, v132
	v_exp_f32_e32 v153, v133
	v_exp_f32_e32 v240, v134
	v_exp_f32_e32 v241, v135
	v_pk_fma_f32 v[132:133], v[138:139], s[58:59], v[200:201] op_sel_hi:[1,0,0] neg_lo:[0,0,1] neg_hi:[0,0,1]
	v_pk_fma_f32 v[134:135], v[154:155], s[58:59], v[200:201] op_sel_hi:[1,0,0] neg_lo:[0,0,1] neg_hi:[0,0,1]
	v_pk_add_f32 v[130:131], v[234:235], v[146:147]
	v_exp_f32_e32 v154, v132
	v_exp_f32_e32 v155, v133
	v_exp_f32_e32 v242, v134
	v_exp_f32_e32 v243, v135
	v_pk_fma_f32 v[132:133], v[140:141], s[58:59], v[200:201] op_sel_hi:[1,0,0] neg_lo:[0,0,1] neg_hi:[0,0,1]
	v_pk_fma_f32 v[134:135], v[156:157], s[58:59], v[200:201] op_sel_hi:[1,0,0] neg_lo:[0,0,1] neg_hi:[0,0,1]
	v_pk_add_f32 v[128:129], v[130:131], v[128:129]
	v_pk_add_f32 v[130:131], v[148:149], v[236:237]
	v_exp_f32_e32 v140, v132
	v_exp_f32_e32 v141, v133
	v_exp_f32_e32 v156, v134
	v_exp_f32_e32 v157, v135
	v_pk_fma_f32 v[132:133], v[142:143], s[58:59], v[200:201] op_sel_hi:[1,0,0] neg_lo:[0,0,1] neg_hi:[0,0,1]
	v_pk_fma_f32 v[134:135], v[158:159], s[58:59], v[200:201] op_sel_hi:[1,0,0] neg_lo:[0,0,1] neg_hi:[0,0,1]
	v_pk_add_f32 v[128:129], v[130:131], v[128:129]
	v_pk_add_f32 v[130:131], v[238:239], v[150:151]
	v_exp_f32_e32 v142, v132
	v_exp_f32_e32 v143, v133
	v_exp_f32_e32 v158, v134
	v_exp_f32_e32 v159, v135
	v_pk_add_f32 v[128:129], v[130:131], v[128:129]
	v_pk_add_f32 v[130:131], v[240:241], v[152:153]
	v_pk_add_f32 v[132:133], v[242:243], v[154:155]
	v_pk_add_f32 v[134:135], v[156:157], v[140:141]
	v_pk_add_f32 v[136:137], v[158:159], v[142:143]
	v_pk_add_f32 v[128:129], v[130:131], v[128:129]
	v_pk_add_f32 v[132:133], v[134:135], v[132:133]
	v_pk_add_f32 v[128:129], v[136:137], v[128:129]
	v_pk_add_f32 v[128:129], v[132:133], v[128:129]
	v_add_f32_e32 v231, v128, v129
	v_fmac_f32_e32 v231, v226, v202
	ds_read_b64_tr_b16 v[128:129], v225 offset:17408
	ds_read_b64_tr_b16 v[130:131], v225 offset:19968
	ds_read_b64_tr_b16 v[138:139], v225 offset:20032
	ds_read_b64_tr_b16 v[136:137], v225 offset:17472
	v_cvt_pk_bf16_f32 v132, v232, v233
	v_cvt_pk_bf16_f32 v133, v146, v147
	v_cvt_pk_bf16_f32 v134, v236, v237
	v_cvt_pk_bf16_f32 v135, v150, v151
	s_waitcnt lgkmcnt(2)
; template <int NS, int SI>
; __device__ __forceinline__ void attn_stream(const unsigned char* kbase, const unsigned char* vbase, const unsigned char* q_rd, bool mask_tail, int last_valid, int hh, float sc,
;                                             f32x16 (&O)[4], float& mrun, float& lrun) {
;     ...
;     __builtin_amdgcn_sched_barrier(0);
;     PV_GROUP(S0, 0, 0) PV_GROUP(S0, 0, 1) PV_GROUP(S1, 1, 0) PV_GROUP(S1, 1, 1)
	s_nop 0
	v_mfma_f32_32x32x16_bf16 v[64:79], v[128:131], v[132:135], v[64:79]
	s_waitcnt lgkmcnt(0)
	v_mfma_f32_32x32x16_bf16 v[48:63], v[136:139], v[132:135], v[48:63]
	ds_read_b64_tr_b16 v[128:129], v225 offset:17536
	ds_read_b64_tr_b16 v[130:131], v225 offset:20096
	ds_read_b64_tr_b16 v[138:139], v225 offset:20160
	ds_read_b64_tr_b16 v[136:137], v225 offset:17600
	s_waitcnt lgkmcnt(2)
	v_mfma_f32_32x32x16_bf16 v[32:47], v[128:131], v[132:135], v[32:47]
	s_waitcnt lgkmcnt(0)
	v_mfma_f32_32x32x16_bf16 v[0:15], v[136:139], v[132:135], v[0:15]
	ds_read_b64_tr_b16 v[128:129], v225 offset:22528
	ds_read_b64_tr_b16 v[130:131], v225 offset:25088
	ds_read_b64_tr_b16 v[138:139], v225 offset:25152
	ds_read_b64_tr_b16 v[136:137], v225 offset:22592
	v_cvt_pk_bf16_f32 v132, v152, v153
	v_cvt_pk_bf16_f32 v133, v154, v155
	v_cvt_pk_bf16_f32 v134, v140, v141
	v_cvt_pk_bf16_f32 v135, v142, v143
	s_waitcnt lgkmcnt(2)
	s_nop 0
	v_mfma_f32_32x32x16_bf16 v[64:79], v[128:131], v[132:135], v[64:79]
	s_waitcnt lgkmcnt(0)
	v_mfma_f32_32x32x16_bf16 v[48:63], v[136:139], v[132:135], v[48:63]
	ds_read_b64_tr_b16 v[128:129], v225 offset:22656
	ds_read_b64_tr_b16 v[130:131], v225 offset:25216
	ds_read_b64_tr_b16 v[138:139], v225 offset:25280
	ds_read_b64_tr_b16 v[136:137], v225 offset:22720
	s_waitcnt lgkmcnt(2)
	v_mfma_f32_32x32x16_bf16 v[32:47], v[128:131], v[132:135], v[32:47]
	s_waitcnt lgkmcnt(0)
	v_mfma_f32_32x32x16_bf16 v[0:15], v[136:139], v[132:135], v[0:15]
	ds_read_b64_tr_b16 v[128:129], v225 offset:27648
	ds_read_b64_tr_b16 v[130:131], v225 offset:30208
	ds_read_b64_tr_b16 v[138:139], v225 offset:30272
	ds_read_b64_tr_b16 v[136:137], v225 offset:27712
	v_cvt_pk_bf16_f32 v132, v144, v145
	v_cvt_pk_bf16_f32 v133, v234, v235
	v_cvt_pk_bf16_f32 v134, v148, v149
	v_cvt_pk_bf16_f32 v135, v238, v239
	s_waitcnt lgkmcnt(2)
	s_nop 0
	v_mfma_f32_32x32x16_bf16 v[64:79], v[128:131], v[132:135], v[64:79]
	s_waitcnt lgkmcnt(0)
	v_mfma_f32_32x32x16_bf16 v[48:63], v[136:139], v[132:135], v[48:63]
	ds_read_b64_tr_b16 v[128:129], v225 offset:27776
	ds_read_b64_tr_b16 v[130:131], v225 offset:30336
	ds_read_b64_tr_b16 v[138:139], v225 offset:30400
	ds_read_b64_tr_b16 v[136:137], v225 offset:27840
	s_waitcnt lgkmcnt(2)
	v_mfma_f32_32x32x16_bf16 v[32:47], v[128:131], v[132:135], v[32:47]
	s_waitcnt lgkmcnt(0)
	v_mfma_f32_32x32x16_bf16 v[0:15], v[136:139], v[132:135], v[0:15]
	ds_read_b64_tr_b16 v[128:129], v225 offset:32768
	ds_read_b64_tr_b16 v[130:131], v225 offset:35328
	ds_read_b64_tr_b16 v[138:139], v225 offset:35392
	ds_read_b64_tr_b16 v[136:137], v225 offset:32832
	v_cvt_pk_bf16_f32 v132, v240, v241
	v_cvt_pk_bf16_f32 v133, v242, v243
	v_cvt_pk_bf16_f32 v134, v156, v157
	v_cvt_pk_bf16_f32 v135, v158, v159
	s_waitcnt lgkmcnt(2)
	s_nop 0
	v_mfma_f32_32x32x16_bf16 v[64:79], v[128:131], v[132:135], v[64:79]
	s_waitcnt lgkmcnt(0)
	v_mfma_f32_32x32x16_bf16 v[48:63], v[136:139], v[132:135], v[48:63]
	ds_read_b64_tr_b16 v[128:129], v225 offset:32896
	ds_read_b64_tr_b16 v[130:131], v225 offset:35456
	ds_read_b64_tr_b16 v[138:139], v225 offset:35520
	ds_read_b64_tr_b16 v[136:137], v225 offset:32960
	s_waitcnt lgkmcnt(2)
	v_mfma_f32_32x32x16_bf16 v[32:47], v[128:131], v[132:135], v[32:47]
	s_waitcnt lgkmcnt(0)
	v_mfma_f32_32x32x16_bf16 v[0:15], v[136:139], v[132:135], v[0:15]
	ds_read_b128 v[144:147], v222 offset:128
	ds_read_b128 v[232:235], v230 offset:160
	ds_read_b128 v[236:239], v222 offset:160
	ds_read_b128 v[148:151], v230 offset:8832
	ds_read_b128 v[240:243], v230 offset:8864
	v_mov_b32_e32 v228, v200
	v_mov_b32_e32 v226, v231

; template <int NS, int SI>
; __device__ __forceinline__ void attn_stream(const unsigned char* kbase, const unsigned char* vbase, const unsigned char* q_rd, bool mask_tail, int last_valid, int hh, float sc,
;                                             f32x16 (&O)[4], float& mrun, float& lrun) {
;     ...
;     float mx = __builtin_amdgcn_fmed3f(S0[0], S1[0], __builtin_inff());
; #pragma unroll
;     for (int r = 1; r < 16; ++r) { mx = __builtin_amdgcn_fmed3f(mx, S0[r], __builtin_inff()); mx = __builtin_amdgcn_fmed3f(mx, S1[r], __builtin_inff()); }
;     mx = fmaxf(mx, __shfl_xor(mx, 32));
;     const float mn = fmaxf(mrun, mx * sc);
;     const float alpha = __builtin_amdgcn_exp2f(mrun - mn);
;     mrun = mn;
;     f32x2 ls2 = {0.f, 0.f};
;     const f32x2 sc2 = {sc, sc}, mn2 = {mn, mn};
; #pragma unroll
;     for (int r = 0; r < 16; r += 2) {
;         const f32x2 t0 = (f32x2){S0[r], S0[r + 1]} * sc2 - mn2, t1 = (f32x2){S1[r], S1[r + 1]} * sc2 - mn2;
;         const f32x2 p0 = {__builtin_amdgcn_exp2f(t0.x), __builtin_amdgcn_exp2f(t0.y)}, p1 = {__builtin_amdgcn_exp2f(t1.x), __builtin_amdgcn_exp2f(t1.y)};
;         S0[r] = p0.x; S0[r + 1] = p0.y; S1[r] = p1.x; S1[r + 1] = p1.y; ls2 += p0 + p1;
;     }
;     lrun = lrun * alpha + (ls2.x + ls2.y);
;     if (__any(alpha != 1.0f)) {
; #pragma unroll
;         for (int d = 0; d < 4; ++d) O[d] = O[d] * alpha;
.LBB0_1177:
	s_nop 9
	v_max3_f32 v200, v128, v129, v130
	v_max3_f32 v202, v144, v145, v146
	v_max3_f32 v200, v200, v131, v132
	v_max3_f32 v202, v202, v147, v148
	v_max3_f32 v200, v200, v133, v134
	v_max3_f32 v202, v202, v149, v150
	v_max3_f32 v200, v200, v135, v136
	v_max3_f32 v202, v202, v151, v152
	v_max3_f32 v200, v200, v137, v138
	v_max3_f32 v202, v202, v153, v154
	v_max3_f32 v200, v200, v139, v140
	v_max3_f32 v202, v202, v155, v156
	v_max3_f32 v200, v200, v141, v142
	v_max3_f32 v202, v202, v157, v158
	v_max3_f32 v200, v200, v143, v159
	v_max_f32_e32 v200, v200, v202
	v_mov_b32_e32 v202, v200
	s_nop 1
	v_permlane32_swap_b32_e32 v202, v200
	v_max_f32_e32 v200, v200, v202
	v_mul_f32_e32 v200, 0x3e38aa3b, v200
	v_max_f32_e32 v200, v229, v200
	v_sub_f32_e32 v202, v200, v229
	v_cmp_lt_f32_e32 vcc, 4.0, v202
	s_nop 1
	v_cndmask_b32_e32 v200, v229, v200, vcc
	v_cmp_neq_f32_e32 vcc, v229, v200
	v_mov_b32_e32 v202, 1.0
	s_cbranch_vccz .LBB0_1179
	v_sub_f32_e32 v202, v229, v200
	v_exp_f32_e32 v202, v202
	s_nop 0
	v_pk_mul_f32 v[126:127], v[126:127], v[202:203] op_sel_hi:[1,0]
	v_pk_mul_f32 v[124:125], v[124:125], v[202:203] op_sel_hi:[1,0]
	v_pk_mul_f32 v[122:123], v[122:123], v[202:203] op_sel_hi:[1,0]
	v_pk_mul_f32 v[120:121], v[120:121], v[202:203] op_sel_hi:[1,0]
	v_pk_mul_f32 v[118:119], v[118:119], v[202:203] op_sel_hi:[1,0]
	v_pk_mul_f32 v[116:117], v[116:117], v[202:203] op_sel_hi:[1,0]
	v_pk_mul_f32 v[114:115], v[114:115], v[202:203] op_sel_hi:[1,0]
	v_pk_mul_f32 v[112:113], v[112:113], v[202:203] op_sel_hi:[1,0]
	v_pk_mul_f32 v[110:111], v[110:111], v[202:203] op_sel_hi:[1,0]
	v_pk_mul_f32 v[108:109], v[108:109], v[202:203] op_sel_hi:[1,0]
	v_pk_mul_f32 v[106:107], v[106:107], v[202:203] op_sel_hi:[1,0]
	v_pk_mul_f32 v[104:105], v[104:105], v[202:203] op_sel_hi:[1,0]
	v_pk_mul_f32 v[102:103], v[102:103], v[202:203] op_sel_hi:[1,0]
	v_pk_mul_f32 v[100:101], v[100:101], v[202:203] op_sel_hi:[1,0]
	v_pk_mul_f32 v[98:99], v[98:99], v[202:203] op_sel_hi:[1,0]
	v_pk_mul_f32 v[96:97], v[96:97], v[202:203] op_sel_hi:[1,0]
	v_pk_mul_f32 v[94:95], v[94:95], v[202:203] op_sel_hi:[1,0]
	v_pk_mul_f32 v[92:93], v[92:93], v[202:203] op_sel_hi:[1,0]
	v_pk_mul_f32 v[90:91], v[90:91], v[202:203] op_sel_hi:[1,0]
	v_pk_mul_f32 v[88:89], v[88:89], v[202:203] op_sel_hi:[1,0]
	v_pk_mul_f32 v[86:87], v[86:87], v[202:203] op_sel_hi:[1,0]
	v_pk_mul_f32 v[84:85], v[84:85], v[202:203] op_sel_hi:[1,0]
	v_pk_mul_f32 v[82:83], v[82:83], v[202:203] op_sel_hi:[1,0]
	v_pk_mul_f32 v[80:81], v[80:81], v[202:203] op_sel_hi:[1,0]
	v_pk_mul_f32 v[30:31], v[30:31], v[202:203] op_sel_hi:[1,0]
	v_pk_mul_f32 v[28:29], v[28:29], v[202:203] op_sel_hi:[1,0]
	v_pk_mul_f32 v[26:27], v[26:27], v[202:203] op_sel_hi:[1,0]
	v_pk_mul_f32 v[24:25], v[24:25], v[202:203] op_sel_hi:[1,0]
	v_pk_mul_f32 v[22:23], v[22:23], v[202:203] op_sel_hi:[1,0]
	v_pk_mul_f32 v[20:21], v[20:21], v[202:203] op_sel_hi:[1,0]
	v_pk_mul_f32 v[18:19], v[18:19], v[202:203] op_sel_hi:[1,0]
	v_pk_mul_f32 v[16:17], v[16:17], v[202:203] op_sel_hi:[1,0]
.LBB0_1179:
	v_pk_fma_f32 v[128:129], v[128:129], s[58:59], v[200:201] op_sel_hi:[1,0,0] neg_lo:[0,0,1] neg_hi:[0,0,1]
	v_pk_fma_f32 v[144:145], v[144:145], s[58:59], v[200:201] op_sel_hi:[1,0,0] neg_lo:[0,0,1] neg_hi:[0,0,1]
	v_exp_f32_e32 v232, v128
	v_exp_f32_e32 v233, v129
	v_exp_f32_e32 v144, v144
	v_exp_f32_e32 v145, v145
	v_pk_fma_f32 v[128:129], v[130:131], s[58:59], v[200:201] op_sel_hi:[1,0,0] neg_lo:[0,0,1] neg_hi:[0,0,1]
	v_pk_fma_f32 v[130:131], v[146:147], s[58:59], v[200:201] op_sel_hi:[1,0,0] neg_lo:[0,0,1] neg_hi:[0,0,1]
	v_exp_f32_e32 v146, v128
	v_exp_f32_e32 v147, v129
	v_exp_f32_e32 v234, v130
	v_exp_f32_e32 v235, v131
	v_pk_fma_f32 v[132:133], v[132:133], s[58:59], v[200:201] op_sel_hi:[1,0,0] neg_lo:[0,0,1] neg_hi:[0,0,1]
	v_pk_fma_f32 v[148:149], v[148:149], s[58:59], v[200:201] op_sel_hi:[1,0,0] neg_lo:[0,0,1] neg_hi:[0,0,1]
	v_exp_f32_e32 v236, v132
	v_exp_f32_e32 v237, v133
	v_exp_f32_e32 v148, v148
	v_exp_f32_e32 v149, v149
	v_pk_fma_f32 v[132:133], v[134:135], s[58:59], v[200:201] op_sel_hi:[1,0,0] neg_lo:[0,0,1] neg_hi:[0,0,1]
	v_pk_fma_f32 v[134:135], v[150:151], s[58:59], v[200:201] op_sel_hi:[1,0,0] neg_lo:[0,0,1] neg_hi:[0,0,1]
	v_exp_f32_e32 v150, v132
	v_exp_f32_e32 v151, v133
	v_exp_f32_e32 v238, v134
	v_exp_f32_e32 v239, v135
	v_pk_fma_f32 v[132:133], v[136:137], s[58:59], v[200:201] op_sel_hi:[1,0,0] neg_lo:[0,0,1] neg_hi:[0,0,1]
	v_pk_fma_f32 v[134:135], v[152:153], s[58:59], v[200:201] op_sel_hi:[1,0,0] neg_lo:[0,0,1] neg_hi:[0,0,1]
	v_pk_add_f32 v[128:129], v[144:145], v[232:233]
	v_exp_f32_e32 v152, v132
	v_exp_f32_e32 v153, v133
	v_exp_f32_e32 v240, v134
	v_exp_f32_e32 v241, v135
	v_pk_fma_f32 v[132:133], v[138:139], s[58:59], v[200:201] op_sel_hi:[1,0,0] neg_lo:[0,0,1] neg_hi:[0,0,1]
	v_pk_fma_f32 v[134:135], v[154:155], s[58:59], v[200:201] op_sel_hi:[1,0,0] neg_lo:[0,0,1] neg_hi:[0,0,1]
	v_pk_add_f32 v[130:131], v[234:235], v[146:147]
	v_exp_f32_e32 v154, v132
	v_exp_f32_e32 v155, v133
	v_exp_f32_e32 v242, v134
	v_exp_f32_e32 v243, v135
	v_pk_fma_f32 v[132:133], v[140:141], s[58:59], v[200:201] op_sel_hi:[1,0,0] neg_lo:[0,0,1] neg_hi:[0,0,1]
	v_pk_fma_f32 v[134:135], v[156:157], s[58:59], v[200:201] op_sel_hi:[1,0,0] neg_lo:[0,0,1] neg_hi:[0,0,1]
	v_pk_add_f32 v[128:129], v[130:131], v[128:129]
	v_pk_add_f32 v[130:131], v[148:149], v[236:237]
	v_exp_f32_e32 v140, v132
	v_exp_f32_e32 v141, v133
	v_exp_f32_e32 v156, v134
	v_exp_f32_e32 v157, v135
	v_pk_fma_f32 v[132:133], v[142:143], s[58:59], v[200:201] op_sel_hi:[1,0,0] neg_lo:[0,0,1] neg_hi:[0,0,1]
	v_pk_fma_f32 v[134:135], v[158:159], s[58:59], v[200:201] op_sel_hi:[1,0,0] neg_lo:[0,0,1] neg_hi:[0,0,1]
	v_pk_add_f32 v[128:129], v[130:131], v[128:129]
	v_pk_add_f32 v[130:131], v[238:239], v[150:151]
	v_exp_f32_e32 v142, v132
	v_exp_f32_e32 v143, v133
	v_exp_f32_e32 v158, v134
	v_exp_f32_e32 v159, v135
	v_pk_add_f32 v[128:129], v[130:131], v[128:129]
	v_pk_add_f32 v[130:131], v[240:241], v[152:153]
	v_pk_add_f32 v[132:133], v[242:243], v[154:155]
	v_pk_add_f32 v[134:135], v[156:157], v[140:141]
	v_pk_add_f32 v[136:137], v[158:159], v[142:143]
	v_pk_add_f32 v[128:129], v[130:131], v[128:129]
	v_pk_add_f32 v[132:133], v[134:135], v[132:133]
	v_pk_add_f32 v[128:129], v[136:137], v[128:129]
	v_pk_add_f32 v[128:129], v[132:133], v[128:129]
	v_add_f32_e32 v230, v128, v129
	v_fmac_f32_e32 v230, v227, v202
	ds_read_b64_tr_b16 v[128:129], v225 offset:17408
	ds_read_b64_tr_b16 v[130:131], v225 offset:19968
	ds_read_b64_tr_b16 v[138:139], v225 offset:20032
	ds_read_b64_tr_b16 v[136:137], v225 offset:17472
	v_cvt_pk_bf16_f32 v132, v232, v233
	v_cvt_pk_bf16_f32 v133, v146, v147
	v_cvt_pk_bf16_f32 v134, v236, v237
	v_cvt_pk_bf16_f32 v135, v150, v151
	s_waitcnt lgkmcnt(2)
; template <int NS, int SI>
; __device__ __forceinline__ void attn_stream(const unsigned char* kbase, const unsigned char* vbase, const unsigned char* q_rd, bool mask_tail, int last_valid, int hh, float sc,
;                                             f32x16 (&O)[4], float& mrun, float& lrun) {
;     ...
;     __builtin_amdgcn_sched_barrier(0);
;     PV_GROUP(S0, 0, 0) PV_GROUP(S0, 0, 1) PV_GROUP(S1, 1, 0) PV_GROUP(S1, 1, 1)
	s_nop 0
	v_mfma_f32_32x32x16_bf16 v[112:127], v[128:131], v[132:135], v[112:127]
	s_waitcnt lgkmcnt(0)
	v_mfma_f32_32x32x16_bf16 v[96:111], v[136:139], v[132:135], v[96:111]
	ds_read_b64_tr_b16 v[128:129], v225 offset:17536
	ds_read_b64_tr_b16 v[130:131], v225 offset:20096
	ds_read_b64_tr_b16 v[138:139], v225 offset:20160
	ds_read_b64_tr_b16 v[136:137], v225 offset:17600
	s_waitcnt lgkmcnt(2)
	v_mfma_f32_32x32x16_bf16 v[80:95], v[128:131], v[132:135], v[80:95]
	s_waitcnt lgkmcnt(0)
	v_mfma_f32_32x32x16_bf16 v[16:31], v[136:139], v[132:135], v[16:31]
	ds_read_b64_tr_b16 v[128:129], v225 offset:22528
	ds_read_b64_tr_b16 v[130:131], v225 offset:25088
	ds_read_b64_tr_b16 v[138:139], v225 offset:25152
	ds_read_b64_tr_b16 v[136:137], v225 offset:22592
	v_cvt_pk_bf16_f32 v132, v152, v153
	v_cvt_pk_bf16_f32 v133, v154, v155
	v_cvt_pk_bf16_f32 v134, v140, v141
	v_cvt_pk_bf16_f32 v135, v142, v143
	s_waitcnt lgkmcnt(2)
	s_nop 0
	v_mfma_f32_32x32x16_bf16 v[112:127], v[128:131], v[132:135], v[112:127]
	s_waitcnt lgkmcnt(0)
	v_mfma_f32_32x32x16_bf16 v[96:111], v[136:139], v[132:135], v[96:111]
	ds_read_b64_tr_b16 v[128:129], v225 offset:22656
	ds_read_b64_tr_b16 v[130:131], v225 offset:25216
	ds_read_b64_tr_b16 v[138:139], v225 offset:25280
	ds_read_b64_tr_b16 v[136:137], v225 offset:22720
	s_waitcnt lgkmcnt(2)
	v_mfma_f32_32x32x16_bf16 v[80:95], v[128:131], v[132:135], v[80:95]
	s_waitcnt lgkmcnt(0)
	v_mfma_f32_32x32x16_bf16 v[16:31], v[136:139], v[132:135], v[16:31]
	ds_read_b64_tr_b16 v[128:129], v225 offset:27648
	ds_read_b64_tr_b16 v[130:131], v225 offset:30208
	ds_read_b64_tr_b16 v[138:139], v225 offset:30272
	ds_read_b64_tr_b16 v[136:137], v225 offset:27712
	v_cvt_pk_bf16_f32 v132, v144, v145
	v_cvt_pk_bf16_f32 v133, v234, v235
	v_cvt_pk_bf16_f32 v134, v148, v149
	v_cvt_pk_bf16_f32 v135, v238, v239
	s_waitcnt lgkmcnt(2)
	s_nop 0
	v_mfma_f32_32x32x16_bf16 v[112:127], v[128:131], v[132:135], v[112:127]
	s_waitcnt lgkmcnt(0)
	v_mfma_f32_32x32x16_bf16 v[96:111], v[136:139], v[132:135], v[96:111]
	ds_read_b64_tr_b16 v[128:129], v225 offset:27776
	ds_read_b64_tr_b16 v[130:131], v225 offset:30336
	ds_read_b64_tr_b16 v[138:139], v225 offset:30400
	ds_read_b64_tr_b16 v[136:137], v225 offset:27840
	s_waitcnt lgkmcnt(2)
	v_mfma_f32_32x32x16_bf16 v[80:95], v[128:131], v[132:135], v[80:95]
	s_waitcnt lgkmcnt(0)
	v_mfma_f32_32x32x16_bf16 v[16:31], v[136:139], v[132:135], v[16:31]
	ds_read_b64_tr_b16 v[128:129], v225 offset:32768
	ds_read_b64_tr_b16 v[130:131], v225 offset:35328
	ds_read_b64_tr_b16 v[138:139], v225 offset:35392
	ds_read_b64_tr_b16 v[136:137], v225 offset:32832
	v_cvt_pk_bf16_f32 v132, v240, v241
	v_cvt_pk_bf16_f32 v133, v242, v243
	v_cvt_pk_bf16_f32 v134, v156, v157
	v_cvt_pk_bf16_f32 v135, v158, v159
	s_waitcnt lgkmcnt(2)
	s_nop 0
	v_mfma_f32_32x32x16_bf16 v[112:127], v[128:131], v[132:135], v[112:127]
	s_waitcnt lgkmcnt(0)
	v_mfma_f32_32x32x16_bf16 v[96:111], v[136:139], v[132:135], v[96:111]
	ds_read_b64_tr_b16 v[128:129], v225 offset:32896
	ds_read_b64_tr_b16 v[130:131], v225 offset:35456
	ds_read_b64_tr_b16 v[138:139], v225 offset:35520
	ds_read_b64_tr_b16 v[136:137], v225 offset:32960
	s_waitcnt lgkmcnt(2)
	v_mfma_f32_32x32x16_bf16 v[80:95], v[128:131], v[132:135], v[80:95]
	s_waitcnt lgkmcnt(0)
	v_mfma_f32_32x32x16_bf16 v[16:31], v[136:139], v[132:135], v[16:31]
	v_mov_b32_e32 v229, v200
	v_mov_b32_e32 v227, v230
	s_or_b64 exec, exec, s[64:65]
	s_and_b64 vcc, exec, s[44:45]
	s_cbranch_vccz .LBB0_1171
	s_branch .LBB0_1172
